# nt8 second measurement
# baseline (speedup 1.0000x reference)
; __device__ __forceinline__ int crow(int r, int hi) { return (r & 3) + 8 * (r >> 2) + 4 * hi; }
;     ...
;   if (hi == 0) li_l[r32] = l_reg; asm volatile("s_waitcnt lgkmcnt(0)" ::: "memory");
;   if constexpr (DIL) { if (hi == 0) lse_o[(long)(wid * QBLK + r32) * lse_s] = m_reg + __log2f(l_reg); }
;   float rli[16];
; #pragma unroll
;   for (int r = 0; r < 16; ++r) rli[r] = __builtin_amdgcn_rcpf(li_l[crow(r, hi)]);
;   bf16* Ow = Ob + (long)(wid * QBLK) * os;
;     ...
;   { char* stg = DIL ? ((wid < 4 ? K_lds : V_lds) + 2 * SHM_K + (wid & 3) * 8192) : (K_lds + wid * 8192);
; #pragma unroll
;     for (int r = 0; r < 16; ++r) { const int orow = crow(r, hi);
; #pragma unroll
;       for (int d0 = 0; d0 < 4; ++d0) *(bf16*)(stg + orow * 256 + (d0 * 32 + r32) * 2) = __float2bfloat16(o[d0][r] * rli[r]); }
.LBB0_136:
	s_or_b64 exec, exec, s[36:37]
	s_lshl_b64 s[0:1], s[0:1], 11
	s_add_u32 s0, s4, s0
	s_addc_u32 s1, s5, s1
	s_lshl_b32 s9, s9, 8
	v_add_u32_e32 v0, s15, v130
	s_add_u32 s10, s0, s9
	ds_read_b128 v[66:69], v0
	ds_read_b128 v[70:73], v0 offset:32
	s_addc_u32 s11, s1, 0
	s_ashr_i32 s23, s22, 31
	s_and_b64 s[0:1], s[2:3], exec
	s_cselect_b32 s2, 12, 14
	s_and_b64 s[0:1], s[18:19], exec
	s_waitcnt lgkmcnt(0)
	v_rcp_f32_e32 v74, v66
	v_rcp_f32_e32 v75, v67
	v_rcp_f32_e32 v76, v68
	v_rcp_f32_e32 v77, v69
	ds_read_b128 v[66:69], v0 offset:64
	s_cselect_b32 s9, 10, s2
	s_lshl_b64 s[0:1], s[22:23], s9
	s_mov_b64 s[2:3], src_shared_base
	s_cmp_lg_u32 0, -1
	s_cselect_b32 s2, 0, 0
	s_cselect_b32 s3, s3, 0
	s_add_u32 s2, s2, 0x8000
	s_waitcnt lgkmcnt(0)
	v_rcp_f32_e32 v78, v66
	v_rcp_f32_e32 v79, v67
	v_rcp_f32_e32 v80, v68
	v_rcp_f32_e32 v81, v69
	ds_read_b128 v[66:69], v0 offset:96
	s_addc_u32 s3, s3, 0
	s_cmp_lg_u64 s[2:3], 0
	s_cselect_b32 s2, s2, -1
	s_cmp_lt_i32 s8, 4
	s_cselect_b32 s2, s2, s90
	s_lshl_b32 s3, s8, 13
	s_and_b32 s3, s3, 0x6000
	s_waitcnt lgkmcnt(0)
	v_rcp_f32_e32 v0, v66
	v_rcp_f32_e32 v66, v67
	v_rcp_f32_e32 v67, v68
	v_rcp_f32_e32 v68, v69
	s_add_i32 s2, s2, s3
	v_lshlrev_b32_e32 v69, 10, v142
	v_lshlrev_b32_e32 v82, 1, v141
	v_mul_f32_e32 v2, v2, v74
	v_add3_u32 v69, s2, v69, v82
	v_cvt_pk_bf16_f32 v2, v2, s0
	ds_write_b16 v69, v2 offset:192
	v_mul_f32_e32 v2, v51, v75
	v_cvt_pk_bf16_f32 v2, v2, s0
	ds_write_b16 v69, v2 offset:256
	v_mul_f32_e32 v2, v35, v75
	v_cvt_pk_bf16_f32 v2, v2, s0
	ds_write_b16 v69, v2 offset:320
	v_mul_f32_e32 v2, v19, v75
	v_cvt_pk_bf16_f32 v2, v2, s0
	ds_write_b16 v69, v2 offset:384
	v_mul_f32_e32 v2, v3, v75
	v_cvt_pk_bf16_f32 v2, v2, s0
	ds_write_b16 v69, v2 offset:448
	v_mul_f32_e32 v2, v52, v76
	v_cvt_pk_bf16_f32 v2, v2, s0
	ds_write_b16 v69, v2 offset:512
	v_mul_f32_e32 v2, v36, v76
	v_cvt_pk_bf16_f32 v2, v2, s0
	ds_write_b16 v69, v2 offset:576
	v_mul_f32_e32 v2, v20, v76
	v_cvt_pk_bf16_f32 v2, v2, s0
	ds_write_b16 v69, v2 offset:640
	v_mul_f32_e32 v2, v4, v76
	v_cvt_pk_bf16_f32 v2, v2, s0
	ds_write_b16 v69, v2 offset:704
	v_mul_f32_e32 v2, v53, v77
	v_cvt_pk_bf16_f32 v2, v2, s0
	ds_write_b16 v69, v2 offset:768
	v_mul_f32_e32 v2, v37, v77
	v_cvt_pk_bf16_f32 v2, v2, s0
	v_rcp_f32_e32 v70, v70
	ds_write_b16 v69, v2 offset:832
	v_mul_f32_e32 v2, v21, v77
	v_cvt_pk_bf16_f32 v2, v2, s0
	ds_write_b16 v69, v2 offset:896
	v_mul_f32_e32 v2, v5, v77
	v_cvt_pk_bf16_f32 v2, v2, s0
	ds_write_b16 v69, v2 offset:960
	v_mul_f32_e32 v2, v54, v70
	v_cvt_pk_bf16_f32 v2, v2, s0
	ds_write_b16 v69, v2 offset:2048
	v_mul_f32_e32 v2, v38, v70
	v_cvt_pk_bf16_f32 v2, v2, s0
	v_rcp_f32_e32 v71, v71
	ds_write_b16 v69, v2 offset:2112
	v_mul_f32_e32 v2, v22, v70
	v_cvt_pk_bf16_f32 v2, v2, s0
	ds_write_b16 v69, v2 offset:2176
	v_mul_f32_e32 v2, v6, v70
	v_cvt_pk_bf16_f32 v2, v2, s0
	ds_write_b16 v69, v2 offset:2240
	v_mul_f32_e32 v2, v55, v71
	v_cvt_pk_bf16_f32 v2, v2, s0
	ds_write_b16 v69, v2 offset:2304
	v_mul_f32_e32 v2, v39, v71
	v_cvt_pk_bf16_f32 v2, v2, s0
	v_rcp_f32_e32 v72, v72
	ds_write_b16 v69, v2 offset:2368
	v_mul_f32_e32 v2, v23, v71
	v_cvt_pk_bf16_f32 v2, v2, s0
	ds_write_b16 v69, v2 offset:2432
	v_mul_f32_e32 v2, v7, v71
	v_cvt_pk_bf16_f32 v2, v2, s0
	ds_write_b16 v69, v2 offset:2496
	v_mul_f32_e32 v2, v56, v72
	v_cvt_pk_bf16_f32 v2, v2, s0
	ds_write_b16 v69, v2 offset:2560
	v_mul_f32_e32 v2, v40, v72
	v_cvt_pk_bf16_f32 v2, v2, s0
	v_rcp_f32_e32 v73, v73
	ds_write_b16 v69, v2 offset:2624
	v_mul_f32_e32 v2, v24, v72
	v_cvt_pk_bf16_f32 v2, v2, s0
	ds_write_b16 v69, v2 offset:2688
	v_mul_f32_e32 v2, v8, v72
	v_cvt_pk_bf16_f32 v2, v2, s0
	ds_write_b16 v69, v2 offset:2752
	v_mul_f32_e32 v2, v57, v73
	v_cvt_pk_bf16_f32 v2, v2, s0
	ds_write_b16 v69, v2 offset:2816
	v_mul_f32_e32 v2, v41, v73
	v_cvt_pk_bf16_f32 v2, v2, s0
	ds_write_b16 v69, v2 offset:2880
	v_mul_f32_e32 v2, v25, v73
	v_cvt_pk_bf16_f32 v2, v2, s0
	ds_write_b16 v69, v2 offset:2944
	v_mul_f32_e32 v2, v9, v73
	v_cvt_pk_bf16_f32 v2, v2, s0
	ds_write_b16 v69, v2 offset:3008
	v_mul_f32_e32 v2, v58, v78
	v_cvt_pk_bf16_f32 v2, v2, s0
	ds_write_b16 v69, v2 offset:4096
	v_mul_f32_e32 v2, v42, v78
	v_cvt_pk_bf16_f32 v2, v2, s0
	ds_write_b16 v69, v2 offset:4160
	v_mul_f32_e32 v2, v26, v78
	v_cvt_pk_bf16_f32 v2, v2, s0
	ds_write_b16 v69, v2 offset:4224
	v_mul_f32_e32 v2, v10, v78
	v_cvt_pk_bf16_f32 v2, v2, s0
	ds_write_b16 v69, v2 offset:4288
	v_mul_f32_e32 v2, v59, v79
	v_cvt_pk_bf16_f32 v2, v2, s0
	ds_write_b16 v69, v2 offset:4352
	v_mul_f32_e32 v2, v43, v79
	v_cvt_pk_bf16_f32 v2, v2, s0
	ds_write_b16 v69, v2 offset:4416
	v_mul_f32_e32 v2, v27, v79
	v_cvt_pk_bf16_f32 v2, v2, s0
	ds_write_b16 v69, v2 offset:4480
	v_mul_f32_e32 v2, v11, v79
	v_cvt_pk_bf16_f32 v2, v2, s0
	ds_write_b16 v69, v2 offset:4544
; __device__ __forceinline__ int crow(int r, int hi) { return (r & 3) + 8 * (r >> 2) + 4 * hi; }
;     ...
;     for (int r = 0; r < 16; ++r) { const int orow = crow(r, hi);
; #pragma unroll
;       for (int d0 = 0; d0 < 4; ++d0) *(bf16*)(stg + orow * 256 + (d0 * 32 + r32) * 2) = __float2bfloat16(o[d0][r] * rli[r]); }
;     asm volatile("s_waitcnt lgkmcnt(0)" ::: "memory");
; #pragma unroll
;     for (int i = 0; i < 8; ++i) { const int row = i * 4 + (lane >> 4), ch = lane & 15;
;       const u32x4 v = *(const u32x4*)(stg + row * 256 + ch * 16);
;       *(u32x4*)(Ow + (long)row * os + ch * 8) = v; } }
	v_mul_f32_e32 v2, v60, v80
	v_cvt_pk_bf16_f32 v2, v2, s0
	ds_write_b16 v69, v2 offset:4608
	v_mul_f32_e32 v2, v44, v80
	v_cvt_pk_bf16_f32 v2, v2, s0
	ds_write_b16 v69, v2 offset:4672
	v_mul_f32_e32 v2, v28, v80
	v_cvt_pk_bf16_f32 v2, v2, s0
	ds_write_b16 v69, v2 offset:4736
	v_mul_f32_e32 v2, v12, v80
	v_cvt_pk_bf16_f32 v2, v2, s0
	ds_write_b16 v69, v2 offset:4800
	v_mul_f32_e32 v2, v61, v81
	v_cvt_pk_bf16_f32 v2, v2, s0
	ds_write_b16 v69, v2 offset:4864
	v_mul_f32_e32 v2, v45, v81
	v_cvt_pk_bf16_f32 v2, v2, s0
	ds_write_b16 v69, v2 offset:4928
	v_mul_f32_e32 v2, v29, v81
	v_cvt_pk_bf16_f32 v2, v2, s0
	ds_write_b16 v69, v2 offset:4992
	v_mul_f32_e32 v2, v13, v81
	v_cvt_pk_bf16_f32 v2, v2, s0
	ds_write_b16 v69, v2 offset:5056
	v_mul_f32_e32 v2, v62, v0
	v_cvt_pk_bf16_f32 v2, v2, s0
	ds_write_b16 v69, v2 offset:6144
	v_mul_f32_e32 v2, v46, v0
	v_cvt_pk_bf16_f32 v2, v2, s0
	ds_write_b16 v69, v2 offset:6208
	v_mul_f32_e32 v2, v30, v0
	v_mul_f32_e32 v0, v14, v0
	v_cvt_pk_bf16_f32 v0, v0, s0
	ds_write_b16 v69, v0 offset:6336
	v_mul_f32_e32 v0, v63, v66
	v_cvt_pk_bf16_f32 v0, v0, s0
	ds_write_b16 v69, v0 offset:6400
	v_mul_f32_e32 v0, v47, v66
	v_cvt_pk_bf16_f32 v0, v0, s0
	ds_write_b16 v69, v0 offset:6464
	v_mul_f32_e32 v0, v31, v66
	v_cvt_pk_bf16_f32 v0, v0, s0
	ds_write_b16 v69, v0 offset:6528
	v_mul_f32_e32 v0, v15, v66
	v_cvt_pk_bf16_f32 v0, v0, s0
	ds_write_b16 v69, v0 offset:6592
	v_mul_f32_e32 v0, v64, v67
	v_cvt_pk_bf16_f32 v0, v0, s0
	ds_write_b16 v69, v0 offset:6656
	v_mul_f32_e32 v0, v48, v67
	v_cvt_pk_bf16_f32 v0, v0, s0
	ds_write_b16 v69, v0 offset:6720
	v_mul_f32_e32 v0, v32, v67
	v_cvt_pk_bf16_f32 v0, v0, s0
	ds_write_b16 v69, v0 offset:6784
	v_mul_f32_e32 v0, v16, v67
	v_cvt_pk_bf16_f32 v0, v0, s0
	ds_write_b16 v69, v0 offset:6848
	v_mul_f32_e32 v0, v65, v68
	v_cvt_pk_bf16_f32 v0, v0, s0
	ds_write_b16 v69, v0 offset:6912
	v_mul_f32_e32 v0, v49, v68
	v_cvt_pk_bf16_f32 v0, v0, s0
	ds_write_b16 v69, v0 offset:6976
	v_mul_f32_e32 v0, v33, v68
	v_cvt_pk_bf16_f32 v0, v0, s0
	v_mul_f32_e32 v50, v50, v74
	v_mul_f32_e32 v34, v34, v74
	v_mul_f32_e32 v18, v18, v74
	ds_write_b16 v69, v0 offset:7040
	v_mul_f32_e32 v0, v17, v68
	v_cvt_pk_bf16_f32 v50, v50, s0
	v_cvt_pk_bf16_f32 v34, v34, s0
	v_cvt_pk_bf16_f32 v18, v18, s0
	v_cvt_pk_bf16_f32 v2, v2, s0
	v_cvt_pk_bf16_f32 v0, v0, s0
	s_lshl_b64 s[0:1], s[0:1], 1
	ds_write_b16 v69, v0 offset:7104
	s_add_u32 s0, s10, s0
	v_lshlrev_b32_e32 v0, 4, v140
	ds_write_b16 v69, v50
	ds_write_b16 v69, v34 offset:64
	ds_write_b16 v69, v18 offset:128
	ds_write_b16 v69, v2 offset:6272
	s_addc_u32 s1, s11, s1
	v_add_u32_e32 v10, s2, v0
	s_waitcnt lgkmcnt(0)
	v_lshl_add_u64 v[6:7], s[0:1], 0, v[0:1]
	v_lshl_add_u32 v0, v131, 8, v10
	ds_read_b128 v[2:5], v0
	v_lshlrev_b32_e32 v0, s9, v131
	v_lshlrev_b32_e32 v0, 1, v0
	v_lshl_add_u64 v[8:9], v[6:7], 0, v[0:1]
	v_or_b32_e32 v0, 4, v131
	s_waitcnt lgkmcnt(0)
	global_store_dwordx4 v[8:9], v[2:5], off nt
	s_add_i32 s99, s99, s98
	s_nop 0
	v_lshl_add_u32 v2, v0, 8, v10
	ds_read_b128 v[2:5], v2
	v_lshlrev_b32_e32 v0, s9, v0
	v_lshlrev_b32_e32 v0, 1, v0
	v_lshl_add_u64 v[8:9], v[6:7], 0, v[0:1]
	v_or_b32_e32 v0, 8, v131
	s_waitcnt lgkmcnt(0)
	global_store_dwordx4 v[8:9], v[2:5], off nt
	s_nop 1
	v_lshl_add_u32 v2, v0, 8, v10
	ds_read_b128 v[2:5], v2
	v_lshlrev_b32_e32 v0, s9, v0
	v_lshlrev_b32_e32 v0, 1, v0
	v_lshl_add_u64 v[8:9], v[6:7], 0, v[0:1]
	v_or_b32_e32 v0, 12, v131
	s_waitcnt lgkmcnt(0)
	global_store_dwordx4 v[8:9], v[2:5], off nt
	s_nop 1
	v_lshl_add_u32 v2, v0, 8, v10
	ds_read_b128 v[2:5], v2
	v_lshlrev_b32_e32 v0, s9, v0
	v_lshlrev_b32_e32 v0, 1, v0
	v_lshl_add_u64 v[8:9], v[6:7], 0, v[0:1]
	v_or_b32_e32 v0, 16, v131
	s_waitcnt lgkmcnt(0)
	global_store_dwordx4 v[8:9], v[2:5], off nt
	s_nop 1
	v_lshl_add_u32 v2, v0, 8, v10
	ds_read_b128 v[2:5], v2
	v_lshlrev_b32_e32 v0, s9, v0
	v_lshlrev_b32_e32 v0, 1, v0
	v_lshl_add_u64 v[8:9], v[6:7], 0, v[0:1]
	v_or_b32_e32 v0, 20, v131
	s_waitcnt lgkmcnt(0)
	global_store_dwordx4 v[8:9], v[2:5], off nt
	s_nop 1
	v_lshl_add_u32 v2, v0, 8, v10
	ds_read_b128 v[2:5], v2
	v_lshlrev_b32_e32 v0, s9, v0
	v_lshlrev_b32_e32 v0, 1, v0
	v_lshl_add_u64 v[8:9], v[6:7], 0, v[0:1]
	v_or_b32_e32 v0, 24, v131
	s_waitcnt lgkmcnt(0)
	global_store_dwordx4 v[8:9], v[2:5], off nt
	s_nop 1
	v_lshl_add_u32 v2, v0, 8, v10
	ds_read_b128 v[2:5], v2
	v_lshlrev_b32_e32 v0, s9, v0
	v_lshlrev_b32_e32 v0, 1, v0
	v_lshl_add_u64 v[8:9], v[6:7], 0, v[0:1]
	v_or_b32_e32 v0, 28, v131
	s_waitcnt lgkmcnt(0)
	global_store_dwordx4 v[8:9], v[2:5], off nt
	s_nop 1
	v_lshl_add_u32 v2, v0, 8, v10
	ds_read_b128 v[2:5], v2
	v_lshlrev_b32_e32 v0, s9, v0
	v_lshlrev_b32_e32 v0, 1, v0
	v_lshl_add_u64 v[6:7], v[6:7], 0, v[0:1]
	s_waitcnt lgkmcnt(0)
	global_store_dwordx4 v[6:7], v[2:5], off nt
	s_waitcnt lgkmcnt(0)
	s_barrier
